# attention: V-tile loads issued at the loop top ahead of Q, V store moved before the softmax
# baseline (speedup 1.0000x reference)
.LBB0_1131:
	s_ashr_i32 s44, s58, 6
	s_and_b32 s4, s58, 63
	s_add_i32 s46, s44, s10
	s_lshr_b32 s47, s4, s62
	s_and_b32 s5, s4, s63
	s_add_i32 s4, s11, s46
	s_waitcnt vmcnt(16)
	v_cvt_f32_i32_e32 v0, s4
	s_lshl_b32 s61, s5, 8
	v_readlane_b32 s4, v253, 56
	s_ashr_i32 s45, s44, 31
	v_mul_f32_e32 v0, 0xbe2aaaab, v0
	v_exp_f32_e32 v0, v0
	s_add_i32 s4, s61, s4
	s_lshl_b64 s[12:13], s[44:45], 14
	s_mul_i32 s45, s47, s41
	s_add_u32 s12, s12, s45
	v_or_b32_e32 v138, s4, v150
	s_addc_u32 s13, s13, 0
	v_mul_f32_e32 v2, v0, v152
	v_lshl_add_u64 v[0:1], s[12:13], 0, v[138:139]
	v_lshlrev_b64 v[0:1], 8, v[0:1]
	s_waitcnt vmcnt(8)
	v_mov_b32_e32 v93, v158
	v_lshl_add_u64 v[0:1], v[132:133], 0, v[0:1]
	s_add_i32 s98, s61, 0xffffff80
	s_ashr_i32 s99, s98, 31
	s_add_u32 s98, s98, s45
	s_addc_u32 s99, s99, 0
	s_lshr_b64 s[98:99], s[98:99], 5
	s_lshl_b64 s[98:99], s[98:99], s53
	s_lshl_b32 s100, s44, 7
	s_ashr_i32 s101, s100, 31
	s_add_u32 s98, s98, s100
	s_addc_u32 s99, s99, s101
	v_lshl_add_u64 v[178:179], s[98:99], 0, v[130:131]
	v_lshlrev_b64 v[178:179], 6, v[178:179]
	v_lshl_add_u64 v[180:181], v[134:135], 0, v[178:179]
	s_mov_b32 s101, s57
	s_cmp_eq_u32 s5, 0
	s_cbranch_scc1 .Lx4_skip4
	global_load_dwordx4 v[204:207], v[180:181], off
	s_mov_b32 s100, s60
	v_lshl_add_u64 v[182:183], v[180:181], 0, s[100:101]
	global_load_dwordx4 v[208:211], v[182:183], off
	s_mov_b32 s100, s64
	v_lshl_add_u64 v[182:183], v[180:181], 0, s[100:101]
	global_load_dwordx4 v[212:215], v[182:183], off
	s_mov_b32 s100, s66
	v_lshl_add_u64 v[182:183], v[180:181], 0, s[100:101]
	global_load_dwordx4 v[184:187], v[182:183], off
.Lx4_skip4:
	s_mov_b32 s100, s56
	v_lshl_add_u64 v[182:183], v[180:181], 0, s[100:101]
	global_load_dwordx4 v[220:223], v[182:183], off
	s_mov_b32 s100, s68
	v_lshl_add_u64 v[182:183], v[180:181], 0, s[100:101]
	global_load_dwordx4 v[224:227], v[182:183], off
	s_mov_b32 s100, s70
	v_lshl_add_u64 v[182:183], v[180:181], 0, s[100:101]
	global_load_dwordx4 v[228:231], v[182:183], off
	s_mov_b32 s100, s72
	v_lshl_add_u64 v[182:183], v[180:181], 0, s[100:101]
	global_load_dwordx4 v[232:235], v[182:183], off
	s_mov_b32 s100, s74
	v_lshl_add_u64 v[182:183], v[180:181], 0, s[100:101]
	global_load_dwordx4 v[236:239], v[182:183], off
	s_mov_b32 s100, s76
	v_lshl_add_u64 v[182:183], v[180:181], 0, s[100:101]
	global_load_dwordx4 v[240:243], v[182:183], off
	s_mov_b32 s100, s78
	v_lshl_add_u64 v[182:183], v[180:181], 0, s[100:101]
	global_load_dwordx4 v[244:247], v[182:183], off
	s_mov_b32 s100, s80
	v_lshl_add_u64 v[182:183], v[180:181], 0, s[100:101]
	global_load_dwordx4 v[248:251], v[182:183], off
	global_load_dwordx4 v[44:47], v[0:1], off
	global_load_dwordx4 v[40:43], v[0:1], off offset:32
	global_load_dwordx4 v[36:39], v[0:1], off offset:64
	global_load_dwordx4 v[32:35], v[0:1], off offset:96
	global_load_dwordx4 v[28:31], v[0:1], off offset:128
	global_load_dwordx4 v[24:27], v[0:1], off offset:160
	global_load_dwordx4 v[20:23], v[0:1], off offset:192
	global_load_dwordx4 v[16:19], v[0:1], off offset:224
	s_cmpk_gt_u32 s4, 0x7f
	s_mov_b32 s50, s94
	v_mul_f32_e32 v92, 0x3fb8aa3b, v2
	v_mov_b32_e32 v48, 0xf149f2ca
	s_cselect_b64 s[48:49], -1, 0
	s_cmpk_lt_u32 s4, 0x80
	v_mov_b32_e32 v84, 0xf149f2ca
	v_mov_b32_e32 v85, 0xf149f2ca
	v_mov_b32_e32 v100, 0xf149f2ca
	v_mov_b32_e32 v102, 0xf149f2ca
	v_mov_b32_e32 v101, 0xf149f2ca
	v_mov_b32_e32 v104, 0xf149f2ca
	v_mov_b32_e32 v103, 0xf149f2ca
	v_mov_b32_e32 v106, 0xf149f2ca
	v_mov_b32_e32 v105, 0xf149f2ca
	v_mov_b32_e32 v108, 0xf149f2ca
	v_mov_b32_e32 v107, 0xf149f2ca
	v_mov_b32_e32 v110, 0xf149f2ca
	v_mov_b32_e32 v109, 0xf149f2ca
	v_mov_b32_e32 v112, 0xf149f2ca
	v_mov_b32_e32 v111, 0xf149f2ca
	v_mov_b32_e32 v114, 0xf149f2ca
	v_mov_b32_e32 v113, 0xf149f2ca
	s_waitcnt lgkmcnt(0)
	s_barrier
	s_cbranch_scc1 .LBB0_1133
	ds_read_b128 v[0:3], v163
	ds_read_b128 v[50:53], v164
	s_mov_b32 s12, 2.0
	s_mov_b32 s13, 0x40400000
	v_cmp_gt_i32_e32 vcc, s67, v93
	s_waitcnt vmcnt(7) lgkmcnt(1)
	v_mfma_f32_32x32x16_bf16 v[0:15], v[0:3], v[44:47], 0
	s_waitcnt vmcnt(6) lgkmcnt(0)
	v_mfma_f32_32x32x16_bf16 v[0:15], v[50:53], v[40:43], v[0:15]
	ds_read_b128 v[50:53], v165
	ds_read_b128 v[54:57], v166
	s_waitcnt vmcnt(5) lgkmcnt(1)
	v_mfma_f32_32x32x16_bf16 v[0:15], v[50:53], v[36:39], v[0:15]
	s_waitcnt vmcnt(4) lgkmcnt(0)
	v_mfma_f32_32x32x16_bf16 v[0:15], v[54:57], v[32:35], v[0:15]
	ds_read_b128 v[50:53], v167
	ds_read_b128 v[54:57], v168
	s_waitcnt vmcnt(3) lgkmcnt(1)
	v_mfma_f32_32x32x16_bf16 v[0:15], v[50:53], v[28:31], v[0:15]
	s_waitcnt vmcnt(2) lgkmcnt(0)
	v_mfma_f32_32x32x16_bf16 v[0:15], v[54:57], v[24:27], v[0:15]
	ds_read_b128 v[50:53], v169
	ds_read_b128 v[54:57], v170
	s_waitcnt vmcnt(1) lgkmcnt(1)
	v_mfma_f32_32x32x16_bf16 v[0:15], v[50:53], v[20:23], v[0:15]
	s_waitcnt vmcnt(0) lgkmcnt(0)
	v_mfma_f32_32x32x16_bf16 v[0:15], v[54:57], v[16:19], v[0:15]
	s_nop 11
	v_pk_fma_f32 v[2:3], v[92:93], s[12:13], v[2:3] op_sel_hi:[0,1,1]
	s_mov_b32 s12, 0x41000000
	s_mov_b32 s13, 0x41100000
	v_pk_fma_f32 v[4:5], v[92:93], s[12:13], v[4:5] op_sel_hi:[0,1,1]
	s_mov_b32 s12, 0x41200000
	s_mov_b32 s13, 0x41300000
	v_pk_fma_f32 v[6:7], v[92:93], s[12:13], v[6:7] op_sel_hi:[0,1,1]
	s_mov_b32 s12, 0x41800000
	s_mov_b32 s13, 0x41880000
	v_pk_fma_f32 v[8:9], v[92:93], s[12:13], v[8:9] op_sel_hi:[0,1,1]
	s_mov_b32 s12, 0x41900000
	s_mov_b32 s13, 0x41980000
	v_pk_fma_f32 v[10:11], v[92:93], s[12:13], v[10:11] op_sel_hi:[0,1,1]
	s_mov_b32 s12, 0x41c00000
	s_mov_b32 s13, 0x41c80000
	v_pk_fma_f32 v[12:13], v[92:93], s[12:13], v[12:13] op_sel_hi:[0,1,1]
	s_mov_b32 s12, 0x41d00000
	s_mov_b32 s13, 0x41d80000
	v_fma_f32 v49, 0, v92, v0
	v_add_f32_e32 v50, v92, v1
	v_pk_fma_f32 v[0:1], v[92:93], s[12:13], v[14:15] op_sel_hi:[0,1,1]
	s_movk_i32 s12, 0x82
	v_cndmask_b32_e32 v85, v175, v49, vcc
	v_cmp_gt_i32_e32 vcc, s12, v93
	s_movk_i32 s12, 0x84
	s_nop 0
	v_cndmask_b32_e32 v100, v175, v50, vcc
	v_cmp_gt_i32_e32 vcc, s12, v93
	s_movk_i32 s12, 0x83
	s_nop 0
	v_cndmask_b32_e32 v101, v175, v3, vcc
	v_cmp_gt_i32_e32 vcc, s12, v93
	s_movk_i32 s12, 0x8a
	s_nop 0
	v_cndmask_b32_e32 v102, v175, v2, vcc
	v_cmp_gt_i32_e32 vcc, s12, v93
	s_movk_i32 s12, 0x89
	s_nop 0
	v_cndmask_b32_e32 v103, v175, v5, vcc
	v_cmp_gt_i32_e32 vcc, s12, v93
	s_movk_i32 s12, 0x8c
	s_nop 0
	v_cndmask_b32_e32 v104, v175, v4, vcc
	v_cmp_gt_i32_e32 vcc, s12, v93
	s_movk_i32 s12, 0x8b
	s_nop 0
	v_cndmask_b32_e32 v105, v175, v7, vcc
	v_cmp_gt_i32_e32 vcc, s12, v93
	s_movk_i32 s12, 0x92
	s_nop 0
	v_cndmask_b32_e32 v106, v175, v6, vcc
	v_cmp_gt_i32_e32 vcc, s12, v93
	s_movk_i32 s12, 0x91
	s_nop 0
	v_cndmask_b32_e32 v107, v175, v9, vcc
	v_cmp_gt_i32_e32 vcc, s12, v93
	s_movk_i32 s12, 0x94
	s_nop 0
	v_cndmask_b32_e32 v108, v175, v8, vcc
	v_cmp_gt_i32_e32 vcc, s12, v93
	s_movk_i32 s12, 0x93
	s_nop 0
	v_cndmask_b32_e32 v109, v175, v11, vcc
	v_cmp_gt_i32_e32 vcc, s12, v93
	s_movk_i32 s12, 0x9a
	s_nop 0
	v_cndmask_b32_e32 v110, v175, v10, vcc
	v_cmp_gt_i32_e32 vcc, s12, v93
	s_movk_i32 s12, 0x99
	s_nop 0
	v_cndmask_b32_e32 v111, v175, v13, vcc
	v_cmp_gt_i32_e32 vcc, s12, v93
	s_movk_i32 s12, 0x9c
	s_nop 0
	v_cndmask_b32_e32 v112, v175, v12, vcc
	v_cmp_gt_i32_e32 vcc, s12, v93
	s_mov_b32 s12, 0xf149f2ca
	s_nop 0
	v_cndmask_b32_e32 v113, v175, v1, vcc
	v_max3_f32 v1, v85, s12, v100
	v_max3_f32 v1, v1, v102, v101
	v_max3_f32 v1, v1, v104, v103
	v_max3_f32 v1, v1, v106, v105
	v_max3_f32 v1, v1, v108, v107
	s_movk_i32 s12, 0x9b
	v_max3_f32 v1, v1, v110, v109
	v_cmp_gt_i32_e32 vcc, s12, v93
	v_max3_f32 v1, v1, v112, v111
	s_nop 0
	v_cndmask_b32_e32 v114, v175, v0, vcc
	v_max3_f32 v84, v1, v114, v113

.LBB0_1142:
	ds_read_b128 v[0:3], v163 offset:32768
	s_movk_i32 s65, 0x7f
	v_cmp_lt_i32_e32 vcc, s65, v93
	s_movk_i32 s65, 0x80
	s_waitcnt vmcnt(7) lgkmcnt(0)
	v_mfma_f32_32x32x16_bf16 v[0:15], v[0:3], v[44:47], 0
	ds_read_b128 v[44:47], v164 offset:32768
	s_waitcnt vmcnt(6) lgkmcnt(0)
	v_mfma_f32_32x32x16_bf16 v[0:15], v[44:47], v[40:43], v[0:15]
	ds_read_b128 v[40:43], v165 offset:32768
	s_waitcnt vmcnt(5) lgkmcnt(0)
	v_mfma_f32_32x32x16_bf16 v[0:15], v[40:43], v[36:39], v[0:15]
	ds_read_b128 v[36:39], v166 offset:32768
	s_waitcnt vmcnt(4) lgkmcnt(0)
	v_mfma_f32_32x32x16_bf16 v[0:15], v[36:39], v[32:35], v[0:15]
	ds_read_b128 v[32:35], v167 offset:32768
	s_waitcnt vmcnt(3) lgkmcnt(0)
	v_mfma_f32_32x32x16_bf16 v[0:15], v[32:35], v[28:31], v[0:15]
	ds_read_b128 v[28:31], v168 offset:32768
	s_waitcnt vmcnt(2) lgkmcnt(0)
	v_mfma_f32_32x32x16_bf16 v[0:15], v[28:31], v[24:27], v[0:15]
	ds_read_b128 v[24:27], v169 offset:32768
	s_waitcnt vmcnt(1) lgkmcnt(0)
	v_mfma_f32_32x32x16_bf16 v[0:15], v[24:27], v[20:23], v[0:15]
	ds_read_b128 v[20:23], v170 offset:32768
	s_waitcnt vmcnt(0) lgkmcnt(0)
	v_mfma_f32_32x32x16_bf16 v[0:15], v[20:23], v[16:19], v[0:15]
	s_nop 11
	v_fmamk_f32 v0, v92, 0x43000000, v0
	v_cndmask_b32_e32 v116, v175, v0, vcc
	v_cmp_lt_i32_e32 vcc, s65, v93
	v_fmamk_f32 v0, v92, 0x43010000, v1
	v_fmamk_f32 v1, v92, 0x43020000, v2
	v_cndmask_b32_e32 v117, v175, v0, vcc
	v_cmp_lt_i32_e32 vcc, s67, v93
	s_movk_i32 s65, 0x82
	v_max3_f32 v0, v115, v116, v117
	v_cndmask_b32_e32 v118, v175, v1, vcc
	v_cmp_lt_i32_e32 vcc, s65, v93
	v_fmamk_f32 v1, v92, 0x43030000, v3
	s_movk_i32 s65, 0x87
	v_cndmask_b32_e32 v142, v175, v1, vcc
	v_cmp_lt_i32_e32 vcc, s65, v93
	v_fmamk_f32 v1, v92, 0x43080000, v4
	s_movk_i32 s65, 0x88
	v_cndmask_b32_e32 v143, v175, v1, vcc
	v_cmp_lt_i32_e32 vcc, s65, v93
	v_fmamk_f32 v1, v92, 0x43090000, v5
	s_movk_i32 s65, 0x89
	v_cndmask_b32_e32 v192, v175, v1, vcc
	v_cmp_lt_i32_e32 vcc, s65, v93
	v_fmamk_f32 v1, v92, 0x430a0000, v6
	s_movk_i32 s65, 0x8a
	v_cndmask_b32_e32 v193, v175, v1, vcc
	v_cmp_lt_i32_e32 vcc, s65, v93
	v_fmamk_f32 v1, v92, 0x430b0000, v7
	s_movk_i32 s65, 0x8f
	v_cndmask_b32_e32 v196, v175, v1, vcc
	v_cmp_lt_i32_e32 vcc, s65, v93
	v_fmamk_f32 v1, v92, 0x43100000, v8
	s_movk_i32 s65, 0x90
	v_cndmask_b32_e32 v197, v175, v1, vcc
	v_cmp_lt_i32_e32 vcc, s65, v93
	v_fmamk_f32 v1, v92, 0x43110000, v9
	s_movk_i32 s65, 0x91
	v_cndmask_b32_e32 v198, v175, v1, vcc
	v_cmp_lt_i32_e32 vcc, s65, v93
	v_fmamk_f32 v1, v92, 0x43120000, v10
	s_movk_i32 s65, 0x92
	v_max3_f32 v0, v0, v118, v142
	v_cndmask_b32_e32 v201, v175, v1, vcc
	v_cmp_lt_i32_e32 vcc, s65, v93
	v_fmamk_f32 v1, v92, 0x43130000, v11
	s_movk_i32 s65, 0x97
	v_max3_f32 v0, v0, v143, v192
	v_cndmask_b32_e32 v203, v175, v1, vcc
	v_cmp_lt_i32_e32 vcc, s65, v93
	v_fmamk_f32 v1, v92, 0x43180000, v12
	s_movk_i32 s65, 0x98
	v_max3_f32 v0, v0, v193, v196
	v_cndmask_b32_e32 v217, v175, v1, vcc
	v_cmp_lt_i32_e32 vcc, s65, v93
	v_fmamk_f32 v1, v92, 0x43190000, v13
	s_movk_i32 s65, 0x99
	v_max3_f32 v0, v0, v197, v198
	v_cndmask_b32_e32 v218, v175, v1, vcc
	v_cmp_lt_i32_e32 vcc, s65, v93
	v_fmamk_f32 v1, v92, 0x431a0000, v14
	s_movk_i32 s65, 0x9a
	v_max3_f32 v0, v0, v201, v203
	v_cndmask_b32_e32 v219, v175, v1, vcc
	v_cmp_lt_i32_e32 vcc, s65, v93
	v_fmac_f32_e32 v15, 0x431b0000, v92
	v_max3_f32 v0, v0, v217, v218
	v_cndmask_b32_e32 v252, v175, v15, vcc
	v_max3_f32 v115, v0, v219, v252
	v_fmac_f32_e32 v115, v92, v159
	v_mov_b32_e32 v119, v115
	s_nop 1
	v_permlane32_swap_b32_e32 v115, v119
	s_addk_i32 s61, 0xff80
	s_ashr_i32 s65, s61, 31
	s_add_u32 s96, s61, s45
	s_addc_u32 s97, s65, 0
	s_lshr_b64 s[96:97], s[96:97], 5
	s_lshl_b64 vcc, s[96:97], s53
	s_lshl_b32 s96, s44, 7
	s_ashr_i32 s97, s96, 31
	s_add_u32 s44, vcc_lo, s96
	s_addc_u32 s45, vcc_hi, s97
	v_lshl_add_u64 v[0:1], s[44:45], 0, v[130:131]
	v_lshlrev_b64 v[0:1], 6, v[0:1]
	s_cmp_lg_u32 s5, 0
	s_cselect_b64 vcc, -1, 0
	s_cmp_eq_u32 s5, 0
	v_lshl_add_u64 v[40:41], v[134:135], 0, v[0:1]
	s_cbranch_scc1 .LBB0_1145
	s_branch .LBB0_1146

.LBB0_1146:
	v_cndmask_b32_e64 v5, 0, 1, vcc
	v_mov_b32_e32 v4, 0
	v_cmp_ne_u32_e64 s[44:45], 1, v5
	s_andn2_b64 vcc, exec, vcc
	v_mov_b32_e32 v8, 0
	v_mov_b32_e32 v9, 0
	v_mov_b32_e32 v10, 0
	v_mov_b32_e32 v11, 0
	s_cbranch_vccnz .LBB0_1148
	s_mov_b32 s61, s57
	v_lshl_add_u64 v[6:7], v[40:41], 0, s[60:61]
.LBB0_1148:
	s_and_b64 vcc, exec, s[44:45]
	v_mov_b32_e32 v5, 0
	v_mov_b32_e32 v6, 0
	v_mov_b32_e32 v7, 0
	s_cbranch_vccnz .LBB0_1150
	s_mov_b32 s65, s57
	v_lshl_add_u64 v[4:5], v[40:41], 0, s[64:65]
.LBB0_1150:
	v_mov_b32_e32 v84, 0
	s_and_b64 vcc, exec, s[44:45]
	v_mov_b32_e32 v12, 0
	v_mov_b32_e32 v13, 0
	v_mov_b32_e32 v14, 0
	v_mov_b32_e32 v15, 0
	s_cbranch_vccnz .LBB0_1152
	s_mov_b32 s67, s57
	v_lshl_add_u64 v[12:13], v[40:41], 0, s[66:67]
	s_movk_i32 s67, 0x81
.LBB0_1152:
	s_mov_b32 s69, s57
	s_mov_b32 s71, s57
	s_mov_b32 s73, s57
	s_mov_b32 s75, s57
	s_mov_b32 s77, s57
	s_mov_b32 s79, s57
	s_mov_b32 s81, s57
	s_barrier
	s_cmp_lg_u32 s5, 0
	s_cbranch_scc1 .Lx4_nz
	v_mov_b32_e32 v204, 0
	v_mov_b32_e32 v205, 0
	v_mov_b32_e32 v206, 0
	v_mov_b32_e32 v207, 0
	v_mov_b32_e32 v208, 0
	v_mov_b32_e32 v209, 0
	v_mov_b32_e32 v210, 0
	v_mov_b32_e32 v211, 0
	v_mov_b32_e32 v212, 0
	v_mov_b32_e32 v213, 0
	v_mov_b32_e32 v214, 0
	v_mov_b32_e32 v215, 0
	v_mov_b32_e32 v184, 0
	v_mov_b32_e32 v185, 0
	v_mov_b32_e32 v186, 0
	v_mov_b32_e32 v187, 0
.Lx4_nz:
	s_waitcnt vmcnt(0)
	ds_write_b128 v161, v[204:207]
	ds_write_b128 v161, v[208:211] offset:64
	ds_write_b128 v161, v[212:215] offset:128
	ds_write_b128 v161, v[184:187] offset:192
	ds_write_b128 v161, v[220:223] offset:256
	ds_write_b128 v161, v[224:227] offset:320
	ds_write_b128 v161, v[228:231] offset:384
	ds_write_b128 v161, v[232:235] offset:448
	ds_write_b128 v161, v[236:239] offset:512
	ds_write_b128 v161, v[240:243] offset:576
	ds_write_b128 v161, v[244:247] offset:640
	ds_write_b128 v161, v[248:251] offset:704
	s_nop 1
	v_max_f32_e32 v115, v115, v115
	v_max_f32_e32 v119, v119, v119
	v_mul_f32_e32 v120, v92, v159
	v_max_f32_e32 v115, v115, v119
	v_sub_f32_e32 v176, v115, v120
	v_pk_add_f32 v[100:101], v[100:101], v[176:177] op_sel_hi:[1,0] neg_lo:[0,1] neg_hi:[0,1]
	v_pk_add_f32 v[102:103], v[102:103], v[176:177] op_sel_hi:[1,0] neg_lo:[0,1] neg_hi:[0,1]
	v_pk_add_f32 v[104:105], v[104:105], v[176:177] op_sel_hi:[1,0] neg_lo:[0,1] neg_hi:[0,1]
	v_pk_add_f32 v[106:107], v[106:107], v[176:177] op_sel_hi:[1,0] neg_lo:[0,1] neg_hi:[0,1]
	v_pk_add_f32 v[108:109], v[108:109], v[176:177] op_sel_hi:[1,0] neg_lo:[0,1] neg_hi:[0,1]
	v_pk_add_f32 v[110:111], v[110:111], v[176:177] op_sel_hi:[1,0] neg_lo:[0,1] neg_hi:[0,1]
	v_pk_add_f32 v[112:113], v[112:113], v[176:177] op_sel_hi:[1,0] neg_lo:[0,1] neg_hi:[0,1]
	v_sub_f32_e32 v85, v85, v176
	v_sub_f32_e32 v114, v114, v176
	v_exp_f32_e32 v237, v85
	v_exp_f32_e32 v240, v100
	v_exp_f32_e32 v241, v102
	v_exp_f32_e32 v244, v101
	v_exp_f32_e32 v245, v104
	v_exp_f32_e32 v248, v103
	v_exp_f32_e32 v249, v106
	v_exp_f32_e32 v251, v105
	v_exp_f32_e32 v236, v108
	v_exp_f32_e32 v238, v107
	v_exp_f32_e32 v239, v110
	v_exp_f32_e32 v242, v109
	v_exp_f32_e32 v243, v112
	v_exp_f32_e32 v246, v111
	v_exp_f32_e32 v247, v114
	v_exp_f32_e32 v250, v113
	s_nop 0
	v_pk_add_f32 v[100:101], v[236:237], v[238:239]
	v_pk_add_f32 v[100:101], v[100:101], v[240:241]
	v_pk_add_f32 v[100:101], v[100:101], v[242:243]
	v_pk_add_f32 v[100:101], v[100:101], v[244:245]
	v_pk_add_f32 v[100:101], v[100:101], v[246:247]
	v_pk_add_f32 v[100:101], v[100:101], v[248:249]
	v_pk_add_f32 v[100:101], v[100:101], v[250:251]
	v_pk_add_f32 v[48:49], v[48:49], v[176:177] op_sel_hi:[1,0] neg_lo:[0,1] neg_hi:[0,1]
	v_pk_add_f32 v[50:51], v[50:51], v[176:177] op_sel_hi:[1,0] neg_lo:[0,1] neg_hi:[0,1]
	v_pk_add_f32 v[52:53], v[52:53], v[176:177] op_sel_hi:[1,0] neg_lo:[0,1] neg_hi:[0,1]
	v_pk_add_f32 v[54:55], v[54:55], v[176:177] op_sel_hi:[1,0] neg_lo:[0,1] neg_hi:[0,1]
	v_pk_add_f32 v[56:57], v[56:57], v[176:177] op_sel_hi:[1,0] neg_lo:[0,1] neg_hi:[0,1]
	v_pk_add_f32 v[58:59], v[58:59], v[176:177] op_sel_hi:[1,0] neg_lo:[0,1] neg_hi:[0,1]
	v_pk_add_f32 v[60:61], v[60:61], v[176:177] op_sel_hi:[1,0] neg_lo:[0,1] neg_hi:[0,1]
	v_pk_add_f32 v[62:63], v[62:63], v[176:177] op_sel_hi:[1,0] neg_lo:[0,1] neg_hi:[0,1]
	v_exp_f32_e32 v220, v48
	v_exp_f32_e32 v221, v49
	v_exp_f32_e32 v222, v50
	v_exp_f32_e32 v223, v51
	v_exp_f32_e32 v224, v52
	v_exp_f32_e32 v225, v53
	v_exp_f32_e32 v226, v54
	v_exp_f32_e32 v227, v55
	v_exp_f32_e32 v228, v56
	v_exp_f32_e32 v229, v57
	v_exp_f32_e32 v230, v58
	v_exp_f32_e32 v231, v59
	v_exp_f32_e32 v232, v60
	v_exp_f32_e32 v233, v61
	v_exp_f32_e32 v234, v62
	v_exp_f32_e32 v235, v63
	s_nop 0
	v_pk_add_f32 v[48:49], v[100:101], v[220:221]
	v_pk_add_f32 v[48:49], v[48:49], v[222:223]
	v_pk_add_f32 v[48:49], v[48:49], v[224:225]
	v_pk_add_f32 v[48:49], v[48:49], v[226:227]
	v_pk_add_f32 v[48:49], v[48:49], v[228:229]
	v_pk_add_f32 v[48:49], v[48:49], v[230:231]
	v_pk_add_f32 v[48:49], v[48:49], v[232:233]
	v_pk_add_f32 v[48:49], v[48:49], v[234:235]
	v_pk_add_f32 v[64:65], v[64:65], v[176:177] op_sel_hi:[1,0] neg_lo:[0,1] neg_hi:[0,1]
	v_pk_add_f32 v[66:67], v[66:67], v[176:177] op_sel_hi:[1,0] neg_lo:[0,1] neg_hi:[0,1]
	v_pk_add_f32 v[68:69], v[68:69], v[176:177] op_sel_hi:[1,0] neg_lo:[0,1] neg_hi:[0,1]
	v_pk_add_f32 v[70:71], v[70:71], v[176:177] op_sel_hi:[1,0] neg_lo:[0,1] neg_hi:[0,1]
	v_pk_add_f32 v[72:73], v[72:73], v[176:177] op_sel_hi:[1,0] neg_lo:[0,1] neg_hi:[0,1]
	v_pk_add_f32 v[74:75], v[74:75], v[176:177] op_sel_hi:[1,0] neg_lo:[0,1] neg_hi:[0,1]
	v_pk_add_f32 v[76:77], v[76:77], v[176:177] op_sel_hi:[1,0] neg_lo:[0,1] neg_hi:[0,1]
	v_pk_add_f32 v[78:79], v[78:79], v[176:177] op_sel_hi:[1,0] neg_lo:[0,1] neg_hi:[0,1]
	v_exp_f32_e32 v199, v64
	v_exp_f32_e32 v200, v65
	v_exp_f32_e32 v202, v66
	v_exp_f32_e32 v204, v67
	v_exp_f32_e32 v205, v68
	v_exp_f32_e32 v206, v69
	v_exp_f32_e32 v207, v70
	v_exp_f32_e32 v208, v71
	v_exp_f32_e32 v209, v72
	v_exp_f32_e32 v210, v73
	v_exp_f32_e32 v211, v74
	v_exp_f32_e32 v212, v75
	v_exp_f32_e32 v213, v76
	v_exp_f32_e32 v214, v77
	v_exp_f32_e32 v215, v78
	v_exp_f32_e32 v216, v79
	s_nop 0
	v_pk_add_f32 v[48:49], v[48:49], v[204:205]
	v_pk_add_f32 v[48:49], v[48:49], v[206:207]
	v_pk_add_f32 v[48:49], v[48:49], v[208:209]
	v_pk_add_f32 v[48:49], v[48:49], v[210:211]
	v_pk_add_f32 v[48:49], v[48:49], v[212:213]
	v_pk_add_f32 v[48:49], v[48:49], v[214:215]
	v_add_f32_e32 v50, 0, v199
	v_add_f32_e32 v50, v50, v200
	v_add_f32_e32 v50, v50, v202
	v_add_f32_e32 v50, v50, v216
	v_pk_add_f32 v[80:81], v[80:81], v[176:177] op_sel_hi:[1,0] neg_lo:[0,1] neg_hi:[0,1]
	v_pk_add_f32 v[82:83], v[82:83], v[176:177] op_sel_hi:[1,0] neg_lo:[0,1] neg_hi:[0,1]
	v_pk_add_f32 v[86:87], v[86:87], v[176:177] op_sel_hi:[1,0] neg_lo:[0,1] neg_hi:[0,1]
	v_pk_add_f32 v[88:89], v[88:89], v[176:177] op_sel_hi:[1,0] neg_lo:[0,1] neg_hi:[0,1]
	v_pk_add_f32 v[90:91], v[90:91], v[176:177] op_sel_hi:[1,0] neg_lo:[0,1] neg_hi:[0,1]
	v_pk_add_f32 v[94:95], v[94:95], v[176:177] op_sel_hi:[1,0] neg_lo:[0,1] neg_hi:[0,1]
	v_pk_add_f32 v[96:97], v[96:97], v[176:177] op_sel_hi:[1,0] neg_lo:[0,1] neg_hi:[0,1]
	v_pk_add_f32 v[98:99], v[98:99], v[176:177] op_sel_hi:[1,0] neg_lo:[0,1] neg_hi:[0,1]
	v_exp_f32_e32 v119, v80
	v_exp_f32_e32 v120, v81
	v_exp_f32_e32 v121, v82
	v_exp_f32_e32 v122, v83
	v_exp_f32_e32 v123, v86
	v_exp_f32_e32 v124, v87
	v_exp_f32_e32 v125, v88
	v_exp_f32_e32 v126, v89
	v_exp_f32_e32 v127, v90
	v_exp_f32_e32 v140, v91
	v_exp_f32_e32 v144, v94
	v_exp_f32_e32 v145, v95
	v_exp_f32_e32 v146, v96
	v_exp_f32_e32 v147, v97
	v_exp_f32_e32 v194, v98
	v_exp_f32_e32 v195, v99
	s_nop 0
	v_pk_add_f32 v[48:49], v[48:49], v[120:121]
	v_pk_add_f32 v[48:49], v[48:49], v[122:123]
	v_pk_add_f32 v[48:49], v[48:49], v[124:125]
	v_pk_add_f32 v[48:49], v[48:49], v[126:127]
	v_pk_add_f32 v[48:49], v[48:49], v[144:145]
	v_pk_add_f32 v[48:49], v[48:49], v[146:147]
	v_pk_add_f32 v[48:49], v[48:49], v[194:195]
	v_add_f32_e32 v50, v50, v119
	v_add_f32_e32 v50, v50, v140
	v_pk_add_f32 v[116:117], v[116:117], v[176:177] op_sel_hi:[1,0] neg_lo:[0,1] neg_hi:[0,1]
	v_pk_add_f32 v[142:143], v[142:143], v[176:177] op_sel_hi:[1,0] neg_lo:[0,1] neg_hi:[0,1]
	v_pk_add_f32 v[192:193], v[192:193], v[176:177] op_sel_hi:[1,0] neg_lo:[0,1] neg_hi:[0,1]
	v_pk_add_f32 v[196:197], v[196:197], v[176:177] op_sel_hi:[1,0] neg_lo:[0,1] neg_hi:[0,1]
	v_pk_add_f32 v[218:219], v[218:219], v[176:177] op_sel_hi:[1,0] neg_lo:[0,1] neg_hi:[0,1]
	v_sub_f32_e32 v118, v118, v176
	v_sub_f32_e32 v198, v198, v176
	v_sub_f32_e32 v201, v201, v176
	v_sub_f32_e32 v203, v203, v176
	v_sub_f32_e32 v217, v217, v176
	v_sub_f32_e32 v252, v252, v176
	v_exp_f32_e32 v100, v116
	v_exp_f32_e32 v101, v117
	v_exp_f32_e32 v102, v118
	v_exp_f32_e32 v103, v142
	v_exp_f32_e32 v104, v143
	v_exp_f32_e32 v105, v192
	v_exp_f32_e32 v106, v193
	v_exp_f32_e32 v107, v196
	v_exp_f32_e32 v108, v197
	v_exp_f32_e32 v109, v198
	v_exp_f32_e32 v110, v201
	v_exp_f32_e32 v111, v203
	v_exp_f32_e32 v112, v217
	v_exp_f32_e32 v113, v218
	v_exp_f32_e32 v114, v219
	v_exp_f32_e32 v116, v252
	s_nop 0
	v_pk_add_f32 v[48:49], v[48:49], v[100:101]
	v_pk_add_f32 v[48:49], v[48:49], v[102:103]
	v_pk_add_f32 v[48:49], v[48:49], v[104:105]
	v_pk_add_f32 v[48:49], v[48:49], v[106:107]
	v_pk_add_f32 v[48:49], v[48:49], v[108:109]
	v_pk_add_f32 v[48:49], v[48:49], v[110:111]
	v_pk_add_f32 v[48:49], v[48:49], v[112:113]
	v_add_f32_e32 v50, v50, v114
	v_add_f32_e32 v50, v50, v116
	v_add_f32_e32 v117, v48, v49
	s_nop 0
	v_add_f32_e32 v117, v117, v50
	v_mov_b32_e32 v0, v149
	s_waitcnt lgkmcnt(0)
	s_barrier
	v_mov_b32_e32 v3, v139
	v_ashrrev_i32_e32 v192, 4, v0
	v_and_b32_e32 v193, 15, v0
	v_add_u32_e32 v0, s4, v192
	s_load_dwordx2 s[4:5], s[8:9], 0x68
	v_lshlrev_b32_e32 v0, s40, v0
	v_add_u32_e32 v94, s47, v0
	v_ashrrev_i32_e32 v95, 31, v94
	v_lshlrev_b64 v[0:1], 12, v[94:95]
	s_waitcnt lgkmcnt(0)
	v_lshl_add_u64 v[0:1], s[4:5], 0, v[0:1]
	s_lshl_b32 s4, s46, 7
	s_ashr_i32 s5, s4, 31
	v_lshl_add_u64 v[0:1], s[4:5], 1, v[0:1]
	v_lshlrev_b32_e32 v2, 4, v193
	v_mov_b32_e32 v118, v117
	v_lshl_add_u64 v[142:143], v[0:1], 0, v[2:3]
	v_cndmask_b32_e64 v0, 0, 1, s[24:25]
	v_permlane32_swap_b32_e32 v117, v118
	v_cmp_ne_u32_e64 s[44:45], 1, v0
	s_andn2_b64 vcc, exec, s[24:25]
	v_mov_b32_e32 v85, 0
	v_mov_b32_e32 v86, 0
	v_mov_b32_e32 v87, 0
	s_cbranch_vccnz .LBB0_1154
	global_load_dwordx4 v[84:87], v[142:143], off
